# all nine GEMM prologues: K-tile 1 LDS-DMA loads issued together with K-tile 0 (before the first wait; wave-row-1 offset barrier moved below them), first wait vmcnt(2)->vmcnt(8)
# speedup vs baseline: 1.0035x; 1.0018x over previous
.LBB0_116:
	s_waitcnt lgkmcnt(6)
	v_add_f32_e32 v8, v8, v10
	v_fmamk_f32 v8, v8, 0x3a800000, v240
	v_rsq_f32_e32 v164, v8
	s_waitcnt lgkmcnt(5)
	v_add_f32_e32 v8, v15, v17
	v_fmamk_f32 v8, v8, 0x3a800000, v240
	v_rsq_f32_e32 v163, v8
	s_waitcnt lgkmcnt(4)
	v_add_f32_e32 v8, v13, v16
	v_fmamk_f32 v8, v8, 0x3a800000, v240
	v_rsq_f32_e32 v162, v8
	s_waitcnt lgkmcnt(3)
	v_add_f32_e32 v8, v12, v14
	v_fmamk_f32 v8, v8, 0x3a800000, v240
	v_rsq_f32_e32 v161, v8
	s_waitcnt lgkmcnt(2)
	v_add_f32_e32 v8, v21, v23
	v_fmamk_f32 v8, v8, 0x3a800000, v240
	v_rsq_f32_e32 v160, v8
	s_waitcnt lgkmcnt(1)
	v_add_f32_e32 v8, v19, v22
	v_fmamk_f32 v8, v8, 0x3a800000, v240
	v_add_f32_e32 v9, v9, v11
	v_rsq_f32_e32 v154, v8
	s_waitcnt lgkmcnt(0)
	v_add_f32_e32 v8, v18, v20
	v_fmamk_f32 v9, v9, 0x3a800000, v240
	v_fmamk_f32 v8, v8, 0x3a800000, v240
	v_rsq_f32_e32 v165, v9
	v_rsq_f32_e32 v151, v8
	v_and_b32_e32 v8, 15, v7
	v_and_b32_e32 v9, 48, v7
	v_lshlrev_b32_e32 v7, 2, v7
	v_mov_b32_e32 v143, v1
	s_and_b32 s59, s6, 3
	v_lshl_or_b32 v8, v8, 6, v9
	s_lshl_b32 s5, s5, 13
	v_and_b32_e32 v7, 32, v7
	v_lshl_add_u64 v[24:25], s[36:37], 0, v[142:143]
	v_mov_b32_e32 v139, v1
	v_bitop3_b32 v10, v8, s5, v7 bitop3:0xde
	s_lshl_b32 s5, s59, 12
	v_lshl_add_u64 v[26:27], s[36:37], 0, v[138:139]
	v_mov_b32_e32 v145, v1
	v_bitop3_b32 v150, v8, s5, v7 bitop3:0xde
	s_add_i32 m0, s52, 0x18000
	v_lshl_add_u64 v[8:9], v[24:25], 0, s[84:85]
	v_lshl_add_u64 v[28:29], s[10:11], 0, v[144:145]
	v_mov_b32_e32 v141, v1
	global_load_lds_dwordx4 v[8:9], off
	v_lshl_add_u64 v[8:9], v[26:27], 0, s[84:85]
	s_add_i32 m0, s52, 0x1a000
	s_add_i32 s60, s52, 0x8000
	s_add_i32 s61, s52, 0xa000
	v_lshl_add_u64 v[30:31], s[10:11], 0, v[140:141]
	global_load_lds_dwordx4 v[8:9], off
	v_lshl_add_u64 v[8:9], v[28:29], 0, s[84:85]
	s_mov_b32 m0, s60
	s_add_u32 s6, s36, 0x40080
	global_load_lds_dwordx4 v[8:9], off
	v_lshl_add_u64 v[8:9], v[30:31], 0, s[84:85]
	s_mov_b32 m0, s61
	s_addc_u32 s7, s37, 0
	global_load_lds_dwordx4 v[8:9], off
	s_add_i32 m0, s52, 0x1c000
	v_lshl_add_u64 v[8:9], s[6:7], 0, v[142:143]
	global_load_lds_dwordx4 v[8:9], off
	v_lshl_add_u64 v[8:9], s[6:7], 0, v[138:139]
	s_add_i32 m0, s52, 0x1e000
	v_lshlrev_b32_e32 v7, 14, v5
	global_load_lds_dwordx4 v[8:9], off
	s_bitcmp1_b32 s97, 8
	s_cbranch_scc0 .Lfill_wr0_0
	s_barrier
.Lfill_wr0_0:
	s_waitcnt vmcnt(8)
	s_barrier
	v_and_b32_e32 v7, 0xffff8000, v7
	v_lshl_add_u32 v4, v4, 11, v7
	v_and_b32_e32 v5, 1, v5
	v_lshl_or_b32 v4, v5, 6, v4
	v_lshl_add_u32 v146, v6, 1, v4
	v_lshlrev_b32_e32 v4, 14, v0
	v_and_b32_e32 v4, 0xffff8000, v4
	s_waitcnt vmcnt(6)
	v_lshl_add_u32 v2, v2, 11, v4
	v_and_b32_e32 v0, 1, v0
	s_cmpk_lt_u32 s4, 0x100
	v_lshl_or_b32 v0, v0, 6, v2
	v_readlane_b32 s6, v253, 7
	s_cselect_b64 s[4:5], -1, 0
	v_mov_b32_e32 v147, v1
	v_lshl_add_u32 v148, v3, 1, v0
	v_mov_b32_e32 v149, v1
	s_mov_b32 s86, 0
	v_add_u32_e32 v152, 0, v10
	v_readlane_b32 s20, v253, 2
	s_mov_b32 s21, s6
	s_barrier
	v_readlane_b32 s7, v253, 8
	s_branch .LBB0_119

.LBB0_139:
	v_readlane_b32 s48, v253, 15
	v_mov_b32_e32 v147, v1
	v_readlane_b32 s49, v253, 16
	v_mov_b32_e32 v143, v1
	v_mov_b32_e32 v149, v1
	v_lshl_add_u64 v[8:9], s[48:49], 0, v[146:147]
	v_lshl_add_u64 v[10:11], s[48:49], 0, v[142:143]
	s_add_i32 m0, s21, 0x18000
	v_lshl_add_u64 v[8:9], v[8:9], 0, s[84:85]
	v_lshl_add_u64 v[12:13], s[40:41], 0, v[148:149]
	v_mov_b32_e32 v145, v1
	global_load_lds_dwordx4 v[8:9], off
	v_lshl_add_u64 v[8:9], v[10:11], 0, s[84:85]
	s_add_i32 m0, s21, 0x1a000
	s_add_i32 s52, s21, 0x8000
	v_lshl_add_u64 v[14:15], s[40:41], 0, v[144:145]
	global_load_lds_dwordx4 v[8:9], off
	v_lshl_add_u64 v[8:9], v[12:13], 0, s[84:85]
	s_mov_b32 m0, s52
	s_add_i32 s53, s21, 0xa000
	v_readlane_b32 s6, v253, 17
	global_load_lds_dwordx4 v[8:9], off
	v_lshl_add_u64 v[8:9], v[14:15], 0, s[84:85]
	s_mov_b32 m0, s53
	v_readlane_b32 s7, v253, 18
	global_load_lds_dwordx4 v[8:9], off
	s_add_i32 m0, s21, 0x1c000
	v_lshl_add_u64 v[8:9], s[6:7], 0, v[146:147]
	global_load_lds_dwordx4 v[8:9], off
	v_lshl_add_u64 v[8:9], s[6:7], 0, v[142:143]
	s_add_i32 m0, s21, 0x1e000
	v_and_b32_e32 v16, 15, v7
	global_load_lds_dwordx4 v[8:9], off
	s_bitcmp1_b32 s97, 8
	s_cbranch_scc0 .Lfill_wr0_1
	s_barrier
.Lfill_wr0_1:
	s_waitcnt vmcnt(8)
	s_barrier
	v_and_b32_e32 v17, 48, v7
	v_lshlrev_b32_e32 v7, 2, v7
	s_and_b32 s25, s5, 3
	v_lshl_or_b32 v16, v16, 6, v17
	s_lshl_b32 s5, s19, 13
	v_and_b32_e32 v7, 32, v7
	v_bitop3_b32 v17, v16, s5, v7 bitop3:0xde
	s_lshl_b32 s5, s25, 12
	v_bitop3_b32 v159, v16, s5, v7 bitop3:0xde
	v_lshlrev_b32_e32 v7, 14, v5
	v_and_b32_e32 v7, 0xffff8000, v7
	v_lshl_add_u32 v4, v4, 11, v7
	v_and_b32_e32 v5, 1, v5
	v_lshl_or_b32 v4, v5, 6, v4
	v_lshl_add_u32 v150, v6, 1, v4
	v_lshlrev_b32_e32 v4, 14, v0
	v_and_b32_e32 v4, 0xffff8000, v4
	s_waitcnt vmcnt(6)
	v_lshl_add_u32 v2, v2, 11, v4
	v_and_b32_e32 v0, 1, v0
	s_cmpk_lt_u32 s4, 0x100
	v_lshl_or_b32 v0, v0, 6, v2
	v_readlane_b32 s6, v253, 35
	s_cselect_b64 s[4:5], -1, 0
	v_mov_b32_e32 v151, v1
	v_lshl_add_u32 v152, v3, 1, v0
	v_mov_b32_e32 v153, v1
	s_mov_b32 s54, 0
	v_add_u32_e32 v161, 0, v17
	v_readlane_b32 s55, v253, 5
	s_mov_b32 s26, s6
	s_barrier
	v_readlane_b32 s7, v253, 36
	s_branch .LBB0_142

.LBB0_163:
	v_mov_b32_e32 v151, v1
	v_lshl_add_u64 v[8:9], s[40:41], 0, v[150:151]
	v_mov_b32_e32 v147, v1
	v_readlane_b32 s10, v253, 63
	v_and_b32_e32 v16, 15, v7
	v_and_b32_e32 v17, 48, v7
	v_lshlrev_b32_e32 v7, 2, v7
	v_lshl_add_u64 v[10:11], s[40:41], 0, v[146:147]
	v_mov_b32_e32 v153, v1
	v_readlane_b32 s11, v254, 0
	s_and_b32 s58, s1, 3
	v_lshl_or_b32 v16, v16, 6, v17
	s_lshl_b32 s1, s50, 13
	v_and_b32_e32 v7, 32, v7
	s_add_i32 m0, s52, 0x18000
	v_lshl_add_u64 v[8:9], v[8:9], 0, s[84:85]
	v_lshl_add_u64 v[12:13], s[10:11], 0, v[152:153]
	v_mov_b32_e32 v149, v1
	v_bitop3_b32 v17, v16, s1, v7 bitop3:0xde
	s_lshl_b32 s1, s58, 12
	global_load_lds_dwordx4 v[8:9], off
	v_lshl_add_u64 v[8:9], v[10:11], 0, s[84:85]
	s_add_i32 m0, s52, 0x1a000
	s_add_i32 s59, s52, 0x8000
	s_add_i32 s60, s52, 0xa000
	v_lshl_add_u64 v[14:15], s[10:11], 0, v[148:149]
	global_load_lds_dwordx4 v[8:9], off
	v_lshl_add_u64 v[8:9], v[12:13], 0, s[84:85]
	s_mov_b32 m0, s59
	s_add_u32 s4, s40, 0x40080
	global_load_lds_dwordx4 v[8:9], off
	v_lshl_add_u64 v[8:9], v[14:15], 0, s[84:85]
	s_mov_b32 m0, s60
	s_addc_u32 s5, s41, 0
	global_load_lds_dwordx4 v[8:9], off
	s_add_i32 m0, s52, 0x1c000
	v_lshl_add_u64 v[8:9], s[4:5], 0, v[150:151]
	global_load_lds_dwordx4 v[8:9], off
	v_lshl_add_u64 v[8:9], s[4:5], 0, v[146:147]
	s_add_i32 m0, s52, 0x1e000
	v_bitop3_b32 v160, v16, s1, v7 bitop3:0xde
	global_load_lds_dwordx4 v[8:9], off
	s_bitcmp1_b32 s97, 8
	s_cbranch_scc0 .Lfill_wr0_2
	s_barrier
.Lfill_wr0_2:
	s_waitcnt vmcnt(8)
	s_barrier
	v_lshlrev_b32_e32 v7, 14, v5
	v_and_b32_e32 v7, 0xffff8000, v7
	v_lshl_add_u32 v4, v4, 11, v7
	v_and_b32_e32 v5, 1, v5
	v_lshl_or_b32 v4, v5, 6, v4
	v_lshl_add_u32 v154, v6, 1, v4
	v_lshlrev_b32_e32 v4, 14, v0
	v_and_b32_e32 v4, 0xffff8000, v4
	s_waitcnt vmcnt(6)
	v_lshl_add_u32 v2, v2, 11, v4
	v_and_b32_e32 v0, 1, v0
	s_cmpk_lt_u32 s0, 0x100
	v_lshl_or_b32 v0, v0, 6, v2
	v_readlane_b32 s0, v253, 58
	s_cselect_b64 s[82:83], -1, 0
	v_mov_b32_e32 v155, v1
	v_lshl_add_u32 v156, v3, 1, v0
	v_mov_b32_e32 v157, v1
	s_mov_b32 s61, 0
	v_add_u32_e32 v161, 0, v17
	v_readlane_b32 s19, v253, 62
	s_mov_b32 s20, s0
	s_barrier
	v_readlane_b32 s1, v253, 59
	s_branch .LBB0_166

.LBB0_261:
	v_lshl_add_u64 v[12:13], s[48:49], 0, v[0:1]
	v_mov_b32_e32 v195, v1
	v_readlane_b32 s50, v253, 37
	v_and_b32_e32 v11, 48, v7
	v_lshlrev_b32_e32 v20, 6, v7
	s_movk_i32 s3, 0x3c0
	v_lshlrev_b32_e32 v7, 2, v7
	v_lshl_add_u64 v[14:15], s[48:49], 0, v[194:195]
	v_mov_b32_e32 v199, v1
	v_readlane_b32 s51, v253, 38
	s_and_b32 s55, s6, 3
	s_lshl_b32 s58, s5, 6
	s_lshl_b32 s5, s5, 13
	v_and_or_b32 v11, v20, s3, v11
	v_and_b32_e32 v7, 32, v7
	s_add_i32 m0, s20, 0x18000
	v_lshl_add_u64 v[12:13], v[12:13], 0, s[84:85]
	v_lshl_add_u64 v[16:17], s[50:51], 0, v[198:199]
	v_mov_b32_e32 v197, v1
	v_bitop3_b32 v20, v11, s5, v7 bitop3:0xde
	s_lshl_b32 s59, s55, 5
	s_lshl_b32 s5, s55, 12
	global_load_lds_dwordx4 v[12:13], off
	v_lshl_add_u64 v[12:13], v[14:15], 0, s[84:85]
	s_add_i32 m0, s20, 0x1a000
	s_add_i32 s60, s20, 0x8000
	s_add_i32 s61, s20, 0xa000
	v_lshl_add_u64 v[18:19], s[50:51], 0, v[196:197]
	global_load_lds_dwordx4 v[12:13], off
	v_lshl_add_u64 v[12:13], v[16:17], 0, s[16:17]
	s_mov_b32 m0, s60
	s_add_u32 s6, s48, 0x100080
	global_load_lds_dwordx4 v[12:13], off
	v_lshl_add_u64 v[12:13], v[18:19], 0, s[16:17]
	s_mov_b32 m0, s61
	s_addc_u32 s7, s49, 0
	global_load_lds_dwordx4 v[12:13], off
	s_add_i32 m0, s20, 0x1c000
	v_lshl_add_u64 v[12:13], s[6:7], 0, v[0:1]
	global_load_lds_dwordx4 v[12:13], off
	v_lshl_add_u64 v[12:13], s[6:7], 0, v[194:195]
	s_add_i32 m0, s20, 0x1e000
	v_bitop3_b32 v242, v11, s5, v7 bitop3:0xde
	global_load_lds_dwordx4 v[12:13], off
	s_bitcmp1_b32 s97, 8
	s_cbranch_scc0 .Lfill_wr0_3
	s_barrier
.Lfill_wr0_3:
	s_waitcnt vmcnt(8)
	s_barrier
	v_lshlrev_b32_e32 v7, 10, v8
	v_lshlrev_b32_e32 v3, 10, v3
	v_and_b32_e32 v7, 0xfffe0000, v7
	v_and_b32_e32 v3, 0xfffe0000, v3
	s_waitcnt vmcnt(6)
	v_lshl_add_u32 v6, v6, 10, v7
	v_lshl_add_u32 v2, v2, 10, v3
	s_cmpk_lt_u32 s4, 0x100
	v_or_b32_e32 v6, v6, v9
	v_or_b32_e32 v2, v2, v4
	v_readlane_b32 s6, v253, 35
	s_cselect_b64 s[4:5], -1, 0
	v_add_u32_e32 v200, v6, v10
	v_mov_b32_e32 v201, v1
	v_add_u32_e32 v202, v2, v5
	v_mov_b32_e32 v203, v1
	s_mov_b32 s24, 0
	v_add_u32_e32 v243, 0, v20
	v_readlane_b32 s25, v253, 5
	s_mov_b32 s26, s6
	s_barrier
	v_readlane_b32 s7, v253, 36
	s_branch .LBB0_264

.LBB0_298:
	v_readlane_b32 s42, v254, 41
	v_and_b32_e32 v3, 15, v2
	v_and_b32_e32 v12, 48, v2
	v_lshlrev_b32_e32 v2, 2, v2
	v_readlane_b32 s43, v254, 42
	s_and_b32 s86, s5, 3
	v_lshl_or_b32 v3, v3, 6, v12
	s_lshl_b32 s5, s25, 13
	v_and_b32_e32 v2, 32, v2
	v_lshl_add_u64 v[4:5], s[42:43], 0, v[0:1]
	v_mov_b32_e32 v131, v1
	v_readlane_b32 s44, v254, 37
	v_bitop3_b32 v12, v3, s5, v2 bitop3:0xde
	s_lshl_b32 s5, s86, 12
	v_lshl_add_u64 v[6:7], s[42:43], 0, v[130:131]
	v_mov_b32_e32 v135, v1
	v_readlane_b32 s45, v254, 38
	v_bitop3_b32 v136, v3, s5, v2 bitop3:0xde
	s_add_i32 m0, s21, 0x18000
	v_lshl_add_u64 v[2:3], v[4:5], 0, s[84:85]
	v_lshl_add_u64 v[8:9], s[44:45], 0, v[134:135]
	v_mov_b32_e32 v133, v1
	global_load_lds_dwordx4 v[2:3], off
	v_lshl_add_u64 v[2:3], v[6:7], 0, s[84:85]
	s_add_i32 m0, s21, 0x1a000
	s_add_i32 s26, s21, 0x8000
	v_lshl_add_u64 v[10:11], s[44:45], 0, v[132:133]
	global_load_lds_dwordx4 v[2:3], off
	v_lshl_add_u64 v[2:3], v[8:9], 0, s[84:85]
	s_mov_b32 m0, s26
	s_add_i32 s27, s21, 0xa000
	v_readlane_b32 s6, v254, 43
	global_load_lds_dwordx4 v[2:3], off
	v_lshl_add_u64 v[2:3], v[10:11], 0, s[84:85]
	s_mov_b32 m0, s27
	v_readlane_b32 s7, v254, 44
	global_load_lds_dwordx4 v[2:3], off
	s_add_i32 m0, s21, 0x1c000
	v_lshl_add_u64 v[2:3], s[6:7], 0, v[0:1]
	global_load_lds_dwordx4 v[2:3], off
	v_lshl_add_u64 v[2:3], s[6:7], 0, v[130:131]
	s_add_i32 m0, s21, 0x1e000
	global_load_lds_dwordx4 v[2:3], off
	s_bitcmp1_b32 s97, 8
	s_cbranch_scc0 .Lfill_wr0_4
	s_barrier
.Lfill_wr0_4:
	s_cmpk_lt_u32 s4, 0x100
	s_waitcnt vmcnt(8)
	s_barrier
	s_waitcnt vmcnt(6)
	v_readlane_b32 s6, v253, 35
	s_mov_b32 s28, 0
	s_cselect_b64 s[4:5], -1, 0
	v_add_u32_e32 v137, 0, v12
	v_readlane_b32 s29, v253, 5
	s_mov_b32 s30, s6
	s_barrier
	v_readlane_b32 s7, v253, 36
	s_branch .LBB0_301

.LBB0_398:
	v_mov_b32_e32 v147, v1
	v_lshl_add_u64 v[8:9], s[48:49], 0, v[146:147]
	v_mov_b32_e32 v143, v1
	v_readlane_b32 s44, v253, 23
	v_and_b32_e32 v16, 15, v7
	v_and_b32_e32 v17, 48, v7
	v_lshlrev_b32_e32 v7, 2, v7
	v_lshl_add_u64 v[10:11], s[48:49], 0, v[142:143]
	v_mov_b32_e32 v149, v1
	v_readlane_b32 s45, v253, 24
	s_and_b32 s52, s7, 3
	v_lshl_or_b32 v16, v16, 6, v17
	s_lshl_b32 s7, s20, 13
	v_and_b32_e32 v7, 32, v7
	s_add_i32 m0, s22, 0x18000
	v_lshl_add_u64 v[8:9], v[8:9], 0, s[84:85]
	v_lshl_add_u64 v[12:13], s[44:45], 0, v[148:149]
	v_mov_b32_e32 v145, v1
	v_bitop3_b32 v17, v16, s7, v7 bitop3:0xde
	s_lshl_b32 s7, s52, 12
	global_load_lds_dwordx4 v[8:9], off
	v_lshl_add_u64 v[8:9], v[10:11], 0, s[84:85]
	s_add_i32 m0, s22, 0x1a000
	s_add_i32 s53, s22, 0x8000
	s_add_i32 s54, s22, 0xa000
	v_lshl_add_u64 v[14:15], s[44:45], 0, v[144:145]
	global_load_lds_dwordx4 v[8:9], off
	v_lshl_add_u64 v[8:9], v[12:13], 0, s[84:85]
	s_mov_b32 m0, s53
	s_add_u32 s8, s48, 0x40080
	global_load_lds_dwordx4 v[8:9], off
	v_lshl_add_u64 v[8:9], v[14:15], 0, s[84:85]
	s_mov_b32 m0, s54
	s_addc_u32 s9, s49, 0
	global_load_lds_dwordx4 v[8:9], off
	s_add_i32 m0, s22, 0x1c000
	v_lshl_add_u64 v[8:9], s[8:9], 0, v[146:147]
	global_load_lds_dwordx4 v[8:9], off
	v_lshl_add_u64 v[8:9], s[8:9], 0, v[142:143]
	s_add_i32 m0, s22, 0x1e000
	v_bitop3_b32 v158, v16, s7, v7 bitop3:0xde
	global_load_lds_dwordx4 v[8:9], off
	s_bitcmp1_b32 s97, 8
	s_cbranch_scc0 .Lfill_wr0_5
	s_barrier
.Lfill_wr0_5:
	s_waitcnt vmcnt(8)
	s_barrier
	v_lshlrev_b32_e32 v7, 14, v5
	v_and_b32_e32 v7, 0xffff8000, v7
	v_lshl_add_u32 v4, v4, 11, v7
	v_and_b32_e32 v5, 1, v5
	v_lshl_or_b32 v4, v5, 6, v4
	v_lshl_add_u32 v150, v6, 1, v4
	v_lshlrev_b32_e32 v4, 14, v0
	v_and_b32_e32 v4, 0xffff8000, v4
	s_waitcnt vmcnt(6)
	v_lshl_add_u32 v2, v2, 11, v4
	v_and_b32_e32 v0, 1, v0
	s_cmpk_lt_u32 s6, 0x100
	v_lshl_or_b32 v0, v0, 6, v2
	v_readlane_b32 s2, v253, 35
	s_cselect_b64 s[6:7], -1, 0
	v_mov_b32_e32 v151, v1
	v_lshl_add_u32 v152, v3, 1, v0
	v_mov_b32_e32 v153, v1
	s_mov_b32 s55, 0
	v_add_u32_e32 v159, 0, v17
	v_readlane_b32 s58, v253, 5
	s_mov_b32 s26, s2
	s_barrier
	v_readlane_b32 s3, v253, 36
	s_branch .LBB0_401

.LBB0_612:
	v_readlane_b32 s44, v254, 49
	v_readlane_b32 s45, v254, 50
	v_mov_b32_e32 v147, v1
	v_readlane_b32 s40, v253, 43
	v_lshl_add_u64 v[26:27], s[44:45], 0, v[0:1]
	v_lshl_add_u64 v[28:29], s[44:45], 0, v[146:147]
	v_mov_b32_e32 v151, v1
	v_readlane_b32 s41, v253, 44
	s_add_i32 m0, s21, 0x18000
	v_lshl_add_u64 v[26:27], v[26:27], 0, s[84:85]
	v_lshl_add_u64 v[30:31], s[40:41], 0, v[150:151]
	v_mov_b32_e32 v149, v1
	global_load_lds_dwordx4 v[26:27], off
	v_lshl_add_u64 v[26:27], v[28:29], 0, s[84:85]
	s_add_i32 m0, s21, 0x1a000
	s_add_i32 s24, s21, 0x8000
	v_lshl_add_u64 v[32:33], s[40:41], 0, v[148:149]
	global_load_lds_dwordx4 v[26:27], off
	v_lshl_add_u64 v[26:27], v[30:31], 0, s[84:85]
	s_mov_b32 m0, s24
	s_add_i32 s25, s21, 0xa000
	v_readlane_b32 s6, v254, 51
	global_load_lds_dwordx4 v[26:27], off
	v_lshl_add_u64 v[26:27], v[32:33], 0, s[84:85]
	s_mov_b32 m0, s25
	v_readlane_b32 s7, v254, 52
	global_load_lds_dwordx4 v[26:27], off
	s_add_i32 m0, s21, 0x1c000
	v_lshl_add_u64 v[26:27], s[6:7], 0, v[0:1]
	global_load_lds_dwordx4 v[26:27], off
	v_lshl_add_u64 v[26:27], s[6:7], 0, v[146:147]
	s_add_i32 m0, s21, 0x1e000
	s_waitcnt lgkmcnt(0)
	v_add_f32_e32 v9, v9, v11
	global_load_lds_dwordx4 v[26:27], off
	s_bitcmp1_b32 s97, 8
	s_cbranch_scc0 .Lfill_wr0_6
	s_barrier
.Lfill_wr0_6:
	s_waitcnt vmcnt(8)
	s_barrier
	v_fmamk_f32 v9, v9, 0x3a800000, v240
	v_rsq_f32_e32 v168, v9
	v_add_f32_e32 v9, v16, v18
	v_fmamk_f32 v9, v9, 0x3a800000, v240
	v_rsq_f32_e32 v166, v9
	v_add_f32_e32 v9, v14, v17
	v_fmamk_f32 v9, v9, 0x3a800000, v240
	v_rsq_f32_e32 v164, v9
	v_add_f32_e32 v9, v13, v15
	v_fmamk_f32 v9, v9, 0x3a800000, v240
	v_rsq_f32_e32 v162, v9
	v_add_f32_e32 v9, v22, v24
	v_fmamk_f32 v9, v9, 0x3a800000, v240
	v_rsq_f32_e32 v160, v9
	v_add_f32_e32 v9, v20, v23
	v_fmamk_f32 v9, v9, 0x3a800000, v240
	v_add_f32_e32 v10, v10, v12
	v_rsq_f32_e32 v158, v9
	v_add_f32_e32 v9, v19, v21
	v_fmamk_f32 v10, v10, 0x3a800000, v240
	v_fmamk_f32 v9, v9, 0x3a800000, v240
	v_rsq_f32_e32 v170, v10
	v_rsq_f32_e32 v156, v9
	v_and_b32_e32 v9, 15, v3
	v_and_b32_e32 v10, 48, v3
	v_lshlrev_b32_e32 v3, 2, v3
	s_and_b32 s52, s5, 3
	v_lshl_or_b32 v9, v9, 6, v10
	s_lshl_b32 s5, s19, 13
	v_and_b32_e32 v3, 32, v3
	v_bitop3_b32 v10, v9, s5, v3 bitop3:0xde
	s_lshl_b32 s5, s52, 12
	v_bitop3_b32 v157, v9, s5, v3 bitop3:0xde
	v_lshlrev_b32_e32 v3, 14, v7
	v_and_b32_e32 v3, 0xffff8000, v3
	v_lshl_add_u32 v3, v6, 11, v3
	v_and_b32_e32 v6, 1, v7
	v_lshl_or_b32 v3, v6, 6, v3
	v_lshl_add_u32 v152, v8, 1, v3
	v_lshlrev_b32_e32 v3, 14, v2
	v_and_b32_e32 v3, 0xffff8000, v3
	s_waitcnt vmcnt(6)
	v_lshl_add_u32 v3, v4, 11, v3
	v_and_b32_e32 v2, 1, v2
	s_cmpk_lt_u32 s4, 0x100
	v_lshl_or_b32 v2, v2, 6, v3
	v_readlane_b32 s6, v253, 47
	s_cselect_b64 s[4:5], -1, 0
	v_mov_b32_e32 v153, v1
	v_lshl_add_u32 v154, v5, 1, v2
	v_mov_b32_e32 v155, v1
	s_mov_b32 s53, 0
	v_add_u32_e32 v159, 0, v10
	v_readlane_b32 s55, v253, 34
	s_mov_b32 s54, s6
	s_barrier
	v_readlane_b32 s7, v253, 48
	s_branch .LBB0_615

.LBB0_810:
	v_and_b32_e32 v9, 48, v8
	v_lshlrev_b32_e32 v18, 6, v8
	s_movk_i32 s3, 0x3c0
	v_lshlrev_b32_e32 v8, 2, v8
	s_and_b32 s54, s8, 3
	s_lshl_b32 s55, s7, 6
	s_lshl_b32 s7, s7, 13
	v_and_or_b32 v9, v18, s3, v9
	v_and_b32_e32 v8, 32, v8
	v_lshl_add_u64 v[10:11], s[42:43], 0, v[0:1]
	v_mov_b32_e32 v215, v1
	v_readlane_b32 s10, v253, 52
	v_bitop3_b32 v18, v9, s7, v8 bitop3:0xde
	s_lshl_b32 s7, s54, 12
	v_lshl_add_u64 v[12:13], s[42:43], 0, v[214:215]
	v_mov_b32_e32 v219, v1
	v_readlane_b32 s11, v253, 53
	v_bitop3_b32 v244, v9, s7, v8 bitop3:0xde
	s_add_i32 m0, s50, 0x18000
	v_lshl_add_u64 v[8:9], v[10:11], 0, s[84:85]
	v_lshl_add_u64 v[14:15], s[10:11], 0, v[218:219]
	v_mov_b32_e32 v217, v1
	s_lshl_b32 s58, s54, 5
	global_load_lds_dwordx4 v[8:9], off
	v_lshl_add_u64 v[8:9], v[12:13], 0, s[84:85]
	s_add_i32 m0, s50, 0x1a000
	s_add_i32 s59, s50, 0x8000
	s_add_i32 s60, s50, 0xa000
	v_lshl_add_u64 v[16:17], s[10:11], 0, v[216:217]
	global_load_lds_dwordx4 v[8:9], off
	v_lshl_add_u64 v[8:9], v[14:15], 0, s[84:85]
	s_mov_b32 m0, s59
	s_add_u32 s8, s42, 0x40080
	global_load_lds_dwordx4 v[8:9], off
	v_lshl_add_u64 v[8:9], v[16:17], 0, s[84:85]
	s_mov_b32 m0, s60
	s_addc_u32 s9, s43, 0
	global_load_lds_dwordx4 v[8:9], off
	s_add_i32 m0, s50, 0x1c000
	v_lshl_add_u64 v[8:9], s[8:9], 0, v[0:1]
	global_load_lds_dwordx4 v[8:9], off
	v_lshl_add_u64 v[8:9], s[8:9], 0, v[214:215]
	s_add_i32 m0, s50, 0x1e000
	global_load_lds_dwordx4 v[8:9], off
	s_bitcmp1_b32 s97, 8
	s_cbranch_scc0 .Lfill_wr0_7
	s_barrier
.Lfill_wr0_7:
	s_cmpk_lt_u32 s6, 0x100
	s_waitcnt vmcnt(8)
	s_barrier
	v_lshlrev_b32_e32 v8, 14, v6
	v_and_b32_e32 v8, 0xffff8000, v8
	v_lshl_add_u32 v5, v5, 11, v8
	v_and_b32_e32 v6, 1, v6
	v_lshl_or_b32 v5, v6, 6, v5
	v_lshl_add_u32 v220, v7, 1, v5
	v_lshlrev_b32_e32 v5, 14, v2
	v_and_b32_e32 v5, 0xffff8000, v5
	s_waitcnt vmcnt(6)
	v_lshl_add_u32 v3, v3, 11, v5
	v_and_b32_e32 v2, 1, v2
	v_lshl_or_b32 v2, v2, 6, v3
	v_readlane_b32 s8, v253, 35
	s_cselect_b64 s[6:7], -1, 0
	v_mov_b32_e32 v221, v1
	v_lshl_add_u32 v222, v4, 1, v2
	v_mov_b32_e32 v223, v1
	s_mov_b32 s61, 0
	v_add_u32_e32 v245, 0, v18
	v_readlane_b32 s20, v253, 5
	s_mov_b32 s21, s8
	s_barrier
	v_readlane_b32 s9, v253, 36
	s_branch .LBB0_813

.LBB0_935:
	s_lshl_b32 s4, s24, 20
	s_and_b32 s4, s4, 0x100000
	v_readlane_b32 s3, v251, 49
	s_add_u32 s4, s3, s4
	v_readlane_b32 s7, v251, 50
	s_addc_u32 s5, s7, 0
	s_lshl_b32 s6, s19, 20
	s_and_b32 s6, s6, 0x100000
	v_readlane_b32 s14, v253, 23
	s_add_u32 s6, s3, s6
	v_mov_b32_e32 v199, v1
	v_readlane_b32 s15, v253, 24
	s_addc_u32 s7, s7, 0
	s_and_b32 s19, s10, 3
	s_add_i32 m0, s55, 0x18000
	v_lshl_add_u64 v[2:3], v[2:3], 0, s[84:85]
	v_lshl_add_u64 v[14:15], s[14:15], 0, v[198:199]
	v_mov_b32_e32 v197, v1
	s_lshl_b32 s61, s9, 6
	s_lshl_b32 s9, s9, 13
	s_lshl_b32 s68, s19, 5
	s_lshl_b32 s13, s19, 12
	global_load_lds_dwordx4 v[2:3], off
	v_lshl_add_u64 v[2:3], v[4:5], 0, s[84:85]
	s_add_i32 m0, s55, 0x1a000
	s_add_i32 s69, s55, 0x8000
	s_add_i32 s80, s55, 0xa000
	v_lshl_add_u64 v[16:17], s[14:15], 0, v[196:197]
	global_load_lds_dwordx4 v[2:3], off
	v_lshl_add_u64 v[2:3], v[14:15], 0, s[84:85]
	s_mov_b32 m0, s69
	s_add_u32 s10, s48, 0x40080
	global_load_lds_dwordx4 v[2:3], off
	v_lshl_add_u64 v[2:3], v[16:17], 0, s[84:85]
	s_mov_b32 m0, s80
	s_addc_u32 s11, s49, 0
	global_load_lds_dwordx4 v[2:3], off
	s_add_i32 m0, s55, 0x1c000
	v_lshl_add_u64 v[2:3], s[10:11], 0, v[0:1]
	global_load_lds_dwordx4 v[2:3], off
	v_lshl_add_u64 v[2:3], s[10:11], 0, v[194:195]
	s_add_i32 m0, s55, 0x1e000
	s_movk_i32 s3, 0x3c0
	global_load_lds_dwordx4 v[2:3], off
	s_bitcmp1_b32 s97, 8
	s_cbranch_scc0 .Lfill_wr0_8
	s_barrier
.Lfill_wr0_8:
	s_waitcnt vmcnt(8)
	s_barrier
	v_and_b32_e32 v2, 48, v7
	v_lshlrev_b32_e32 v3, 6, v7
	v_and_or_b32 v2, v3, s3, v2
	v_lshlrev_b32_e32 v3, 2, v7
	v_and_b32_e32 v3, 32, v3
	v_bitop3_b32 v4, v2, s9, v3 bitop3:0xde
	v_bitop3_b32 v212, v2, s13, v3 bitop3:0xde
	v_lshlrev_b32_e32 v2, 14, v11
	v_and_b32_e32 v2, 0xffff8000, v2
	v_lshl_add_u32 v2, v10, 11, v2
	v_and_b32_e32 v3, 1, v11
	v_lshl_or_b32 v2, v3, 6, v2
	v_lshl_add_u32 v200, v12, 1, v2
	v_lshlrev_b32_e32 v2, 14, v6
	v_and_b32_e32 v2, 0xffff8000, v2
	s_waitcnt vmcnt(6)
	v_lshl_add_u32 v2, v8, 11, v2
	v_and_b32_e32 v3, 1, v6
	v_readlane_b32 s10, v253, 35
	s_cmpk_lt_u32 s8, 0x100
	v_lshl_or_b32 v2, v3, 6, v2
	v_readlane_b32 s11, v253, 36
	s_mov_b32 s12, s24
	s_cselect_b64 s[8:9], -1, 0
	v_mov_b32_e32 v201, v1
	v_lshl_add_u32 v202, v9, 1, v2
	v_mov_b32_e32 v203, v1
	s_mov_b32 s81, 0
	v_add_u32_e32 v213, 0, v4
	v_readlane_b32 s82, v253, 5
	s_mov_b32 s20, s10
	s_mov_b64 s[10:11], s[14:15]
	s_barrier
	s_branch .LBB0_938
